# cand28 + P2 sample-row tail: next stage's LayerNorm-parameter loads issued with this stage's gate loads (one round trip per stage)
# speedup vs baseline: 1.0129x; 1.0045x over previous
.LBB0_601:
	s_ashr_i32 s0, s25, 6
	s_add_i32 s2, s0, s81
	s_cmp_gt_i32 s2, 31
	s_cbranch_scc1 .LBB0_603
	s_ashr_i32 s3, s2, 31
	s_lshl_b64 s[0:1], s[2:3], 15
	v_and_b32_e32 v1, 63, v1
	s_waitcnt lgkmcnt(0)
	s_add_u32 s0, s14, s0
	s_waitcnt vmcnt(3)
	v_mov_b32_e32 v67, 0
	s_addc_u32 s1, s15, s1
	v_lshlrev_b32_e32 v66, 4, v1
	v_lshl_add_u64 v[68:69], s[0:1], 0, v[66:67]
	s_mov_b64 s[0:1], 0x69984000
	v_lshl_add_u64 v[2:3], v[68:69], 0, s[0:1]
	s_mov_b32 s1, 0x69986000
	v_add_co_u32_e32 v4, vcc, s1, v68
	s_mov_b32 s0, 0x69985000
	s_nop 0
	v_addc_co_u32_e32 v5, vcc, 0, v69, vcc
	v_add_co_u32_e32 v6, vcc, s0, v68
	global_load_dwordx4 v[58:61], v[2:3], off offset:1024
	global_load_dwordx4 v[50:53], v[2:3], off offset:2048
	v_addc_co_u32_e32 v7, vcc, 0, v69, vcc
	global_load_dwordx4 v[46:49], v[4:5], off offset:-4096
	global_load_dwordx4 v[42:45], v[6:7], off offset:1024
	global_load_dwordx4 v[38:41], v[6:7], off offset:2048
	global_load_dwordx4 v[34:37], v[6:7], off offset:3072
	v_add_co_u32_e32 v6, vcc, 0x69984000, v68
	global_load_dwordx4 v[30:33], v[4:5], off
	global_load_dwordx4 v[26:29], v[4:5], off offset:1024
	v_addc_co_u32_e32 v7, vcc, 0, v69, vcc
	global_load_dwordx4 v[62:65], v[6:7], off
	global_load_dwordx4 v[54:57], v[2:3], off offset:3072
	global_load_dwordx4 v[22:25], v[4:5], off offset:2048
	s_mov_b32 s0, 0x69987000
	global_load_dwordx4 v[18:21], v[4:5], off offset:3072
	v_add_co_u32_e32 v70, vcc, s0, v68
	s_mov_b32 s0, 0xf800000
	s_nop 0
	v_addc_co_u32_e32 v71, vcc, 0, v69, vcc
	global_load_dwordx4 v[14:17], v[70:71], off
	global_load_dwordx4 v[10:13], v[70:71], off offset:1024
	global_load_dwordx4 v[6:9], v[70:71], off offset:2048
	global_load_dwordx4 v[2:5], v[70:71], off offset:3072
	s_waitcnt vmcnt(15)
	v_mov_b32_e32 v70, v59
	v_mov_b32_e32 v71, v60
	v_mov_b32_e32 v72, v58
	v_mov_b32_e32 v73, v61
	s_waitcnt vmcnt(13)
	v_mov_b32_e32 v78, v47
	v_mov_b32_e32 v79, v48
	v_mov_b32_e32 v80, v46
	v_mov_b32_e32 v81, v49
	s_waitcnt vmcnt(12)
	v_add_f32_e32 v82, v42, v43
	v_add_f32_e32 v84, v44, v45
	s_waitcnt vmcnt(11)
	v_mov_b32_e32 v83, v40
	v_mov_b32_e32 v85, v41
	s_waitcnt vmcnt(10)
	v_mov_b32_e32 v86, v35
	v_mov_b32_e32 v87, v36
	v_mov_b32_e32 v88, v34
	v_mov_b32_e32 v89, v37
	s_waitcnt vmcnt(7)
	v_mov_b32_e32 v94, v63
	v_mov_b32_e32 v95, v64
	v_mov_b32_e32 v96, v62
	v_mov_b32_e32 v97, v65
	v_pk_add_f32 v[70:71], v[70:71], v[72:73]
	v_pk_add_f32 v[78:79], v[78:79], v[80:81]
	v_pk_add_f32 v[80:81], v[82:83], v[84:85]
	v_pk_add_f32 v[82:83], v[86:87], v[88:89]
	v_pk_add_f32 v[86:87], v[94:95], v[96:97]
	v_pk_add_f32 v[70:71], v[70:71], v[70:71] op_sel:[0,1] op_sel_hi:[1,0]
	v_add_f32_e32 v72, v86, v87
	v_add_f32_e32 v74, v50, v51
	v_add_f32_e32 v76, v52, v53
	s_waitcnt vmcnt(6)
	v_mov_b32_e32 v73, v54
	v_mov_b32_e32 v75, v56
	v_mov_b32_e32 v77, v57
	v_mov_b32_e32 v71, v55
	v_add_f32_e32 v72, 0, v72
	v_pk_add_f32 v[74:75], v[74:75], v[76:77]
	v_pk_add_f32 v[70:71], v[72:73], v[70:71]
	v_pk_add_f32 v[76:77], v[78:79], v[78:79] op_sel:[0,1] op_sel_hi:[1,0]
	v_pk_add_f32 v[70:71], v[70:71], v[74:75]
	v_mov_b32_e32 v77, v39
	v_pk_add_f32 v[70:71], v[70:71], v[70:71] op_sel:[0,1] op_sel_hi:[1,0]
	v_pk_add_f32 v[78:79], v[82:83], v[82:83] op_sel:[0,1] op_sel_hi:[1,0]
	v_mov_b32_e32 v71, v38
	v_pk_add_f32 v[70:71], v[70:71], v[76:77]
	v_add_f32_e32 v90, v30, v31
	v_pk_add_f32 v[70:71], v[70:71], v[80:81]
	v_add_f32_e32 v92, v32, v33
	v_pk_add_f32 v[70:71], v[70:71], v[70:71] op_sel:[0,1] op_sel_hi:[1,0]
	v_mov_b32_e32 v91, v28
	v_mov_b32_e32 v93, v29
	v_mov_b32_e32 v79, v27
	v_mov_b32_e32 v71, v26
	v_pk_add_f32 v[84:85], v[90:91], v[92:93]
	v_pk_add_f32 v[70:71], v[70:71], v[78:79]
	s_waitcnt vmcnt(5)
	v_mov_b32_e32 v72, v23
	v_mov_b32_e32 v73, v24
	v_mov_b32_e32 v74, v22
	v_mov_b32_e32 v75, v25
	v_pk_add_f32 v[70:71], v[70:71], v[84:85]
	v_pk_add_f32 v[72:73], v[72:73], v[74:75]
	v_pk_add_f32 v[70:71], v[70:71], v[70:71] op_sel:[0,1] op_sel_hi:[1,0]
	v_pk_add_f32 v[72:73], v[72:73], v[72:73] op_sel:[0,1] op_sel_hi:[1,0]
	s_waitcnt vmcnt(4)
	v_add_f32_e32 v74, v18, v19
	v_add_f32_e32 v76, v20, v21
	s_waitcnt vmcnt(3)
	v_mov_b32_e32 v71, v14
	v_mov_b32_e32 v73, v15
	v_mov_b32_e32 v75, v16
	v_mov_b32_e32 v77, v17
	v_pk_add_f32 v[70:71], v[70:71], v[72:73]
	v_pk_add_f32 v[72:73], v[74:75], v[76:77]
	s_waitcnt vmcnt(2)
	v_mov_b32_e32 v74, v10
	v_pk_add_f32 v[70:71], v[70:71], v[72:73]
	v_mov_b32_e32 v72, v11
	v_mov_b32_e32 v73, v12
	v_mov_b32_e32 v75, v13
	v_pk_add_f32 v[72:73], v[72:73], v[74:75]
	v_pk_add_f32 v[70:71], v[70:71], v[70:71] op_sel:[0,1] op_sel_hi:[1,0]
	v_pk_add_f32 v[72:73], v[72:73], v[72:73] op_sel:[0,1] op_sel_hi:[1,0]
	s_waitcnt vmcnt(1)
	v_add_f32_e32 v74, v6, v7
	v_add_f32_e32 v76, v8, v9
	s_waitcnt vmcnt(0)
	v_mov_b32_e32 v71, v2
	v_mov_b32_e32 v73, v3
	v_mov_b32_e32 v75, v4
	v_mov_b32_e32 v77, v5
	v_pk_add_f32 v[70:71], v[70:71], v[72:73]
	v_pk_add_f32 v[72:73], v[74:75], v[76:77]
	s_nop 0
	v_pk_add_f32 v[70:71], v[70:71], v[72:73]
	s_nop 0
	v_add_f32_e32 v70, v70, v71
	v_mbcnt_hi_u32_b32 v71, -1, v234
	v_and_b32_e32 v72, 64, v71
	v_add_u32_e32 v72, 64, v72
	v_xor_b32_e32 v73, 1, v71
	v_cmp_lt_i32_e32 vcc, v73, v72
	s_nop 1
	v_cndmask_b32_e32 v73, v71, v73, vcc
	v_lshlrev_b32_e32 v78, 2, v73
	s_waitcnt lgkmcnt(0)
	s_nop 1
	v_add_f32_dpp v70, v70, v70 quad_perm:[1,0,3,2] row_mask:0xf bank_mask:0xf
	v_xor_b32_e32 v73, 2, v71
	v_cmp_lt_i32_e32 vcc, v73, v72
	s_nop 1
	v_cndmask_b32_e32 v73, v71, v73, vcc
	v_lshlrev_b32_e32 v84, 2, v73
	s_waitcnt lgkmcnt(0)
	s_nop 1
	v_add_f32_dpp v70, v70, v70 quad_perm:[2,3,0,1] row_mask:0xf bank_mask:0xf
	v_xor_b32_e32 v73, 4, v71
	v_cmp_lt_i32_e32 vcc, v73, v72
	s_nop 1
	v_cndmask_b32_e32 v73, v71, v73, vcc
	v_lshlrev_b32_e32 v85, 2, v73
	s_waitcnt lgkmcnt(0)
	s_nop 1
	v_add_f32_dpp v70, v70, v70 row_half_mirror row_mask:0xf bank_mask:0xf
	v_xor_b32_e32 v73, 8, v71
	v_cmp_lt_i32_e32 vcc, v73, v72
	s_nop 1
	v_cndmask_b32_e32 v73, v71, v73, vcc
	v_lshlrev_b32_e32 v86, 2, v73
	s_waitcnt lgkmcnt(0)
	s_nop 1
	v_add_f32_dpp v70, v70, v70 row_mirror row_mask:0xf bank_mask:0xf
	v_xor_b32_e32 v73, 16, v71
	v_cmp_lt_i32_e32 vcc, v73, v72
	s_nop 1
	v_cndmask_b32_e32 v73, v71, v73, vcc
	v_lshlrev_b32_e32 v87, 2, v73
	s_waitcnt lgkmcnt(0)
	v_mov_b32_e32 v73, v70
	s_nop 1
	v_permlane16_swap_b32_e32 v73, v70
	v_add_f32_e32 v70, v70, v73
	v_xor_b32_e32 v73, 32, v71
	v_cmp_lt_i32_e32 vcc, v73, v72
	s_nop 1
	v_cndmask_b32_e32 v71, v71, v73, vcc
	v_lshlrev_b32_e32 v88, 2, v71
	s_waitcnt lgkmcnt(0)
	v_mov_b32_e32 v79, v70
	v_mov_b32_e32 v71, v70
	s_nop 1
	v_permlane32_swap_b32_e32 v71, v79
	v_add_f32_e32 v79, v79, v71
	v_fmamk_f32 v75, v79, 0xb9800000, v63
	v_fmamk_f32 v74, v79, 0xb9800000, v62
	v_fmamk_f32 v65, v79, 0xb9800000, v65
	v_fmac_f32_e32 v64, 0xb9800000, v79
	v_pk_mul_f32 v[62:63], v[64:65], v[64:65]
	v_pk_mul_f32 v[70:71], v[74:75], v[74:75]
	v_fmamk_f32 v61, v79, 0xb9800000, v61
	v_pk_mov_b32 v[72:73], v[70:71], v[62:63] op_sel:[1,0]
	v_mov_b32_e32 v71, v63
	v_pk_add_f32 v[62:63], v[72:73], v[70:71]
	v_fmamk_f32 v73, v79, 0xb9800000, v59
	v_fmamk_f32 v72, v79, 0xb9800000, v58
	v_fmac_f32_e32 v60, 0xb9800000, v79
	v_pk_mul_f32 v[58:59], v[60:61], v[60:61]
	v_pk_mul_f32 v[70:71], v[72:73], v[72:73]
	v_fmac_f32_e32 v54, 0xb9800000, v79
	v_pk_mov_b32 v[76:77], v[70:71], v[58:59] op_sel:[1,0]
	v_mov_b32_e32 v71, v59
	v_pk_add_f32 v[76:77], v[76:77], v[70:71]
	v_fmamk_f32 v71, v79, 0xb9800000, v51
	v_fmamk_f32 v70, v79, 0xb9800000, v50
	v_fmamk_f32 v58, v79, 0xb9800000, v56
	v_fmamk_f32 v55, v79, 0xb9800000, v55
	v_mul_f32_e32 v56, v54, v54
	v_pk_add_f32 v[50:51], v[62:63], v[62:63] op_sel:[0,1] op_sel_hi:[1,0]
	v_fmamk_f32 v59, v79, 0xb9800000, v57
	v_mul_f32_e32 v80, v55, v55
	v_mov_b32_e32 v51, v56
	v_pk_add_f32 v[56:57], v[76:77], v[76:77] op_sel:[0,1] op_sel_hi:[1,0]
	v_fmamk_f32 v53, v79, 0xb9800000, v53
	v_mov_b32_e32 v57, v80
	v_fmac_f32_e32 v52, 0xb9800000, v79
	v_pk_add_f32 v[50:51], v[50:51], v[56:57]
	v_mul_f32_e32 v56, v71, v71
	v_mul_f32_e32 v62, v53, v53
	v_mul_f32_e32 v81, v58, v58
	v_mul_f32_e32 v82, v59, v59
	v_pk_fma_f32 v[56:57], v[70:71], v[70:71], v[56:57] op_sel_hi:[1,1,0]
	v_pk_fma_f32 v[62:63], v[52:53], v[52:53], v[62:63] op_sel_hi:[1,1,0]
	v_mov_b32_e32 v57, v81
	v_mov_b32_e32 v63, v82
	v_pk_add_f32 v[56:57], v[56:57], v[62:63]
	v_fmamk_f32 v49, v79, 0xb9800000, v49
	v_pk_add_f32 v[62:63], v[50:51], v[56:57]
	v_fmamk_f32 v57, v79, 0xb9800000, v47
	v_fmamk_f32 v56, v79, 0xb9800000, v46
	v_fmac_f32_e32 v48, 0xb9800000, v79
	v_pk_mul_f32 v[46:47], v[48:49], v[48:49]
	v_pk_mul_f32 v[50:51], v[56:57], v[56:57]
	v_fmac_f32_e32 v38, 0xb9800000, v79
	v_pk_mov_b32 v[76:77], v[50:51], v[46:47] op_sel:[1,0]
	v_mov_b32_e32 v51, v47
	v_pk_add_f32 v[76:77], v[76:77], v[50:51]
	v_fmamk_f32 v50, v79, 0xb9800000, v42
	v_fmamk_f32 v47, v79, 0xb9800000, v41
	v_fmamk_f32 v46, v79, 0xb9800000, v40
	v_fmamk_f32 v39, v79, 0xb9800000, v39
	v_mul_f32_e32 v42, v38, v38
	v_pk_add_f32 v[40:41], v[62:63], v[62:63] op_sel:[0,1] op_sel_hi:[1,0]
	v_fmamk_f32 v51, v79, 0xb9800000, v43
	v_mul_f32_e32 v80, v39, v39
	v_mov_b32_e32 v41, v42
	v_pk_add_f32 v[42:43], v[76:77], v[76:77] op_sel:[0,1] op_sel_hi:[1,0]
	v_fmamk_f32 v45, v79, 0xb9800000, v45
	v_mov_b32_e32 v43, v80
	v_fmac_f32_e32 v44, 0xb9800000, v79
	v_pk_add_f32 v[40:41], v[40:41], v[42:43]
	v_mul_f32_e32 v42, v51, v51
	v_mul_f32_e32 v62, v45, v45
	v_mul_f32_e32 v81, v46, v46
	v_mul_f32_e32 v82, v47, v47
	v_pk_fma_f32 v[42:43], v[50:51], v[50:51], v[42:43] op_sel_hi:[1,1,0]
	v_pk_fma_f32 v[62:63], v[44:45], v[44:45], v[62:63] op_sel_hi:[1,1,0]
	v_mov_b32_e32 v43, v81
	v_mov_b32_e32 v63, v82
	v_pk_add_f32 v[42:43], v[42:43], v[62:63]
	v_fmamk_f32 v37, v79, 0xb9800000, v37
	v_pk_add_f32 v[62:63], v[40:41], v[42:43]
	v_fmamk_f32 v43, v79, 0xb9800000, v35
	v_fmamk_f32 v42, v79, 0xb9800000, v34
	v_fmac_f32_e32 v36, 0xb9800000, v79
	v_pk_mul_f32 v[34:35], v[36:37], v[36:37]
	v_pk_mul_f32 v[40:41], v[42:43], v[42:43]
	v_fmac_f32_e32 v26, 0xb9800000, v79
	v_pk_mov_b32 v[76:77], v[40:41], v[34:35] op_sel:[1,0]
	v_mov_b32_e32 v41, v35
	v_pk_add_f32 v[76:77], v[76:77], v[40:41]
	v_fmamk_f32 v40, v79, 0xb9800000, v30
	v_fmamk_f32 v35, v79, 0xb9800000, v29
	v_fmamk_f32 v34, v79, 0xb9800000, v28
	v_fmamk_f32 v27, v79, 0xb9800000, v27
	v_mul_f32_e32 v30, v26, v26
	v_pk_add_f32 v[28:29], v[62:63], v[62:63] op_sel:[0,1] op_sel_hi:[1,0]
	v_fmamk_f32 v41, v79, 0xb9800000, v31
	v_mul_f32_e32 v80, v27, v27
	v_mov_b32_e32 v29, v30
	v_pk_add_f32 v[30:31], v[76:77], v[76:77] op_sel:[0,1] op_sel_hi:[1,0]
	v_fmamk_f32 v33, v79, 0xb9800000, v33
	v_mov_b32_e32 v31, v80
	v_fmac_f32_e32 v32, 0xb9800000, v79
	v_pk_add_f32 v[28:29], v[28:29], v[30:31]
	v_mul_f32_e32 v30, v41, v41
	v_mul_f32_e32 v62, v33, v33
	v_mul_f32_e32 v81, v34, v34
	v_mul_f32_e32 v82, v35, v35
	v_pk_fma_f32 v[30:31], v[40:41], v[40:41], v[30:31] op_sel_hi:[1,1,0]
	v_pk_fma_f32 v[62:63], v[32:33], v[32:33], v[62:63] op_sel_hi:[1,1,0]
	v_mov_b32_e32 v31, v81
	v_mov_b32_e32 v63, v82
	v_pk_add_f32 v[30:31], v[30:31], v[62:63]
	v_fmamk_f32 v25, v79, 0xb9800000, v25
	v_pk_add_f32 v[28:29], v[28:29], v[30:31]
	v_fmamk_f32 v31, v79, 0xb9800000, v23
	v_fmamk_f32 v30, v79, 0xb9800000, v22
	v_fmac_f32_e32 v24, 0xb9800000, v79
	v_pk_mul_f32 v[22:23], v[24:25], v[24:25]
	v_pk_mul_f32 v[62:63], v[30:31], v[30:31]
	v_fmamk_f32 v15, v79, 0xb9800000, v15
	v_pk_mov_b32 v[76:77], v[62:63], v[22:23] op_sel:[1,0]
	v_mov_b32_e32 v63, v23
	v_pk_add_f32 v[62:63], v[76:77], v[62:63]
	v_fmac_f32_e32 v14, 0xb9800000, v79
	v_fmamk_f32 v23, v79, 0xb9800000, v19
	v_fmamk_f32 v22, v79, 0xb9800000, v18
	v_mul_f32_e32 v76, v14, v14
	v_mul_f32_e32 v77, v15, v15
	v_pk_add_f32 v[18:19], v[28:29], v[28:29] op_sel:[0,1] op_sel_hi:[1,0]
	v_pk_add_f32 v[28:29], v[62:63], v[62:63] op_sel:[0,1] op_sel_hi:[1,0]
	v_fmamk_f32 v21, v79, 0xb9800000, v21
	v_mov_b32_e32 v19, v76
	v_mov_b32_e32 v29, v77
	v_fmac_f32_e32 v20, 0xb9800000, v79
	v_fmamk_f32 v17, v79, 0xb9800000, v17
	v_fmamk_f32 v16, v79, 0xb9800000, v16
	v_pk_add_f32 v[18:19], v[18:19], v[28:29]
	v_mul_f32_e32 v28, v23, v23
	v_mul_f32_e32 v62, v21, v21
	v_mul_f32_e32 v80, v16, v16
	v_mul_f32_e32 v81, v17, v17
	v_pk_fma_f32 v[28:29], v[22:23], v[22:23], v[28:29] op_sel_hi:[1,1,0]
	v_pk_fma_f32 v[62:63], v[20:21], v[20:21], v[62:63] op_sel_hi:[1,1,0]
	v_mov_b32_e32 v29, v80
	v_mov_b32_e32 v63, v81
	v_pk_add_f32 v[28:29], v[28:29], v[62:63]
	v_fmamk_f32 v11, v79, 0xb9800000, v11
	v_fmamk_f32 v10, v79, 0xb9800000, v10
	v_fmamk_f32 v13, v79, 0xb9800000, v13
	v_fmac_f32_e32 v12, 0xb9800000, v79
	v_pk_add_f32 v[18:19], v[18:19], v[28:29]
	v_pk_mul_f32 v[28:29], v[12:13], v[12:13]
	v_pk_mul_f32 v[62:63], v[10:11], v[10:11]
	v_fmamk_f32 v3, v79, 0xb9800000, v3
	v_pk_mov_b32 v[76:77], v[62:63], v[28:29] op_sel:[1,0]
	v_mov_b32_e32 v63, v29
	v_pk_add_f32 v[28:29], v[76:77], v[62:63]
	v_fmac_f32_e32 v2, 0xb9800000, v79
	v_mul_f32_e32 v62, v2, v2
	v_mul_f32_e32 v63, v3, v3
	v_pk_add_f32 v[18:19], v[18:19], v[18:19] op_sel:[0,1] op_sel_hi:[1,0]
	v_pk_add_f32 v[28:29], v[28:29], v[28:29] op_sel:[0,1] op_sel_hi:[1,0]
	v_fmamk_f32 v7, v79, 0xb9800000, v7
	v_fmamk_f32 v9, v79, 0xb9800000, v9
	v_mov_b32_e32 v19, v62
	v_mov_b32_e32 v29, v63
	v_fmamk_f32 v6, v79, 0xb9800000, v6
	v_fmac_f32_e32 v8, 0xb9800000, v79
	v_fmamk_f32 v5, v79, 0xb9800000, v5
	v_fmamk_f32 v4, v79, 0xb9800000, v4
	v_pk_add_f32 v[18:19], v[18:19], v[28:29]
	v_mul_f32_e32 v28, v7, v7
	v_mul_f32_e32 v62, v9, v9
	v_mul_f32_e32 v76, v4, v4
	v_mul_f32_e32 v77, v5, v5
	v_pk_fma_f32 v[28:29], v[6:7], v[6:7], v[28:29] op_sel_hi:[1,1,0]
	v_pk_fma_f32 v[62:63], v[8:9], v[8:9], v[62:63] op_sel_hi:[1,1,0]
	v_mov_b32_e32 v29, v76
	v_mov_b32_e32 v63, v77
	v_pk_add_f32 v[28:29], v[28:29], v[62:63]
	s_nop 0
	v_pk_add_f32 v[18:19], v[18:19], v[28:29]
	s_nop 0
	v_add_f32_e32 v18, v18, v19
	global_load_dwordx4 v[76:79], v66, s[4:5]
	global_load_dwordx4 v[80:83], v66, s[6:7]
	s_waitcnt lgkmcnt(0)
	s_nop 1
	v_add_f32_dpp v18, v18, v18 quad_perm:[1,0,3,2] row_mask:0xf bank_mask:0xf
	s_waitcnt lgkmcnt(0)
	s_nop 1
	v_add_f32_dpp v18, v18, v18 quad_perm:[2,3,0,1] row_mask:0xf bank_mask:0xf
	s_waitcnt lgkmcnt(0)
	s_nop 1
	v_add_f32_dpp v18, v18, v18 row_half_mirror row_mask:0xf bank_mask:0xf
	v_lshlrev_b32_e32 v86, 3, v1
	v_mov_b32_e32 v1, 0x10000
	s_waitcnt lgkmcnt(0)
	s_nop 1
	v_add_f32_dpp v18, v18, v18 row_mirror row_mask:0xf bank_mask:0xf
	v_mov_b32_e32 v87, v67
	s_waitcnt lgkmcnt(0)
	v_mov_b32_e32 v19, v18
	s_nop 1
	v_permlane16_swap_b32_e32 v19, v18
	v_add_f32_e32 v18, v18, v19
	s_waitcnt lgkmcnt(0)
	v_mov_b32_e32 v19, v18
	s_nop 1
	v_permlane32_swap_b32_e32 v19, v18
	v_add_f32_e32 v18, v18, v19
	v_mov_b32_e32 v19, 0x358637bd
	v_fmac_f32_e32 v19, 0x39800000, v18
	v_mul_f32_e32 v18, 0x4f800000, v19
	v_cmp_gt_f32_e32 vcc, s0, v19
	s_nop 1
	v_cndmask_b32_e32 v18, v19, v18, vcc
	v_sqrt_f32_e32 v19, v18
	s_nop 0
	v_add_u32_e32 v28, -1, v19
	v_fma_f32 v29, -v28, v19, v18
	v_cmp_ge_f32_e64 s[0:1], 0, v29
	v_add_u32_e32 v29, 1, v19
	s_nop 0
	v_cndmask_b32_e64 v28, v19, v28, s[0:1]
	v_fma_f32 v19, -v29, v19, v18
	v_cmp_lt_f32_e64 s[0:1], 0, v19
	s_nop 1
	v_cndmask_b32_e64 v19, v28, v29, s[0:1]
	v_mul_f32_e32 v28, 0x37800000, v19
	v_cndmask_b32_e32 v19, v19, v28, vcc
	v_mov_b32_e32 v28, 0x260
	v_cmp_class_f32_e32 vcc, v18, v28
	s_nop 1
	v_cndmask_b32_e32 v18, v19, v18, vcc
	v_div_scale_f32 v19, s[0:1], v18, v18, 1.0
	v_rcp_f32_e32 v28, v19
	s_lshl_b64 s[0:1], s[2:3], 14
	s_add_u32 s0, s12, s0
	s_addc_u32 s1, s13, s1
	v_fma_f32 v29, -v19, v28, 1.0
	v_fmac_f32_e32 v28, v29, v28
	v_div_scale_f32 v29, vcc, 1.0, v18, 1.0
	v_mul_f32_e32 v62, v29, v28
	v_fma_f32 v63, -v19, v62, v29
	v_fmac_f32_e32 v62, v63, v28
	v_fma_f32 v19, -v19, v62, v29
	v_div_fmas_f32 v19, v19, v28, v62
	v_div_fixup_f32 v18, v19, v18, 1.0
	v_lshl_add_u64 v[62:63], s[0:1], 0, v[66:67]
	v_pk_mul_f32 v[64:65], v[18:19], v[64:65] op_sel_hi:[0,1]
	s_mov_b32 s0, 0x8881000
	v_pk_mul_f32 v[28:29], v[18:19], v[74:75] op_sel_hi:[0,1]
	s_waitcnt vmcnt(0)
	v_pk_fma_f32 v[78:79], v[78:79], v[64:65], v[82:83]
	v_add_co_u32_e32 v64, vcc, s0, v62
	v_pk_fma_f32 v[76:77], v[76:77], v[28:29], v[80:81]
	s_nop 0
	v_addc_co_u32_e32 v65, vcc, 0, v63, vcc
	s_mov_b32 s0, 0x69981000
	global_store_dwordx4 v[64:65], v[76:79], off offset:-4096
	v_add_co_u32_e32 v74, vcc, s0, v68
	global_load_dword v28, v67, s[8:9]
	global_load_dword v84, v67, s[10:11]
	v_addc_co_u32_e32 v75, vcc, 0, v69, vcc
	global_load_dwordx4 v[80:83], v[74:75], off offset:-4096
	v_add_u32_e32 v186, 0x400, v66
	global_load_dwordx4 v[178:181], v186, s[4:5]
	global_load_dwordx4 v[182:185], v186, s[6:7]
	s_lshl_b64 s[0:1], s[2:3], 13
	s_add_u32 s0, s14, s0
	s_addc_u32 s1, s15, s1
	v_lshl_add_u64 v[86:87], s[0:1], 0, v[86:87]
	s_mov_b32 s0, 0x69a81000
	s_mov_b64 s[2:3], 0x8880000
	v_pk_mul_f32 v[60:61], v[18:19], v[60:61] op_sel_hi:[0,1]
	v_pk_mul_f32 v[72:73], v[18:19], v[72:73] op_sel_hi:[0,1]
	v_pk_mul_f32 v[52:53], v[18:19], v[52:53] op_sel_hi:[0,1]
	v_pk_mul_f32 v[70:71], v[18:19], v[70:71] op_sel_hi:[0,1]
	v_pk_mul_f32 v[58:59], v[18:19], v[58:59] op_sel_hi:[0,1]
	v_pk_mul_f32 v[48:49], v[18:19], v[48:49] op_sel_hi:[0,1]
	v_pk_mul_f32 v[56:57], v[18:19], v[56:57] op_sel_hi:[0,1]
	v_pk_mul_f32 v[44:45], v[18:19], v[44:45] op_sel_hi:[0,1]
	v_pk_mul_f32 v[46:47], v[18:19], v[46:47] op_sel_hi:[0,1]
	v_pk_mul_f32 v[38:39], v[18:19], v[38:39] op_sel_hi:[0,1]
	s_waitcnt vmcnt(3)
	v_pk_fma_f32 v[76:77], v[76:77], v[28:29], v[84:85] op_sel_hi:[1,0,0]
	v_pk_fma_f32 v[28:29], v[78:79], v[28:29], v[84:85] op_sel_hi:[1,0,0]
	v_lshl_add_u64 v[84:85], v[62:63], 0, s[2:3]
	s_waitcnt vmcnt(2)
	v_pk_mul_f32 v[28:29], v[82:83], v[28:29]
	v_pk_mul_f32 v[76:77], v[80:81], v[76:77]
	s_nop 0
	v_cvt_pk_bf16_f32 v76, v76, v77
	v_cvt_pk_bf16_f32 v77, v28, v29
	v_add_co_u32_e32 v28, vcc, s0, v86
	s_mov_b64 s[0:1], 0x69980000
	s_nop 0
	v_addc_co_u32_e32 v29, vcc, 0, v87, vcc
	global_store_dwordx2 v[28:29], v[76:77], off offset:-4096
	s_waitcnt vmcnt(1)
	v_mov_b64_e32 v[76:77], v[178:179]
	v_mov_b64_e32 v[78:79], v[180:181]
	s_nop 0
	v_mov_b64_e32 v[80:81], v[182:183]
	v_mov_b64_e32 v[82:83], v[184:185]
	v_lshl_add_u64 v[90:91], v[68:69], 0, s[0:1]
	s_mov_b64 s[0:1], 0x69a80000
	v_pk_fma_f32 v[76:77], v[76:77], v[72:73], v[80:81]
	v_pk_fma_f32 v[78:79], v[78:79], v[60:61], v[82:83]
	global_store_dwordx4 v[84:85], v[76:79], off offset:1024
	global_load_dword v72, v1, s[8:9]
	global_load_dword v88, v67, s[10:11] offset:512
	global_load_dwordx4 v[80:83], v[90:91], off offset:1024
	v_add_u32_e32 v186, 0x800, v66
	global_load_dwordx4 v[178:181], v186, s[4:5]
	global_load_dwordx4 v[182:185], v186, s[6:7]
	v_lshl_add_u64 v[60:61], v[86:87], 0, s[0:1]
	v_mov_b32_e32 v1, 0x20000
	s_mov_b32 s0, 0x8883000
	s_mov_b32 s1, 0x69983000
	s_waitcnt vmcnt(3)
	v_pk_fma_f32 v[76:77], v[76:77], v[72:73], v[88:89] op_sel_hi:[1,0,0]
	v_pk_fma_f32 v[72:73], v[78:79], v[72:73], v[88:89] op_sel_hi:[1,0,0]
	s_waitcnt vmcnt(2)
	v_pk_mul_f32 v[76:77], v[80:81], v[76:77]
	v_pk_mul_f32 v[72:73], v[82:83], v[72:73]
	v_cvt_pk_bf16_f32 v76, v76, v77
	s_nop 0
	v_cvt_pk_bf16_f32 v77, v72, v73
	global_store_dwordx2 v[60:61], v[76:77], off offset:512
	s_waitcnt vmcnt(1)
	v_mov_b64_e32 v[76:77], v[178:179]
	v_mov_b64_e32 v[78:79], v[180:181]
	s_nop 0
	v_mov_b64_e32 v[80:81], v[182:183]
	v_mov_b64_e32 v[82:83], v[184:185]
	v_pk_fma_f32 v[70:71], v[76:77], v[70:71], v[80:81]
	v_pk_fma_f32 v[72:73], v[78:79], v[52:53], v[82:83]
	global_store_dwordx4 v[84:85], v[70:73], off offset:2048
	global_load_dword v52, v1, s[8:9]
	global_load_dword v80, v67, s[10:11] offset:1024
	global_load_dwordx4 v[76:79], v[90:91], off offset:2048
	v_add_u32_e32 v186, 0xc00, v66
	global_load_dwordx4 v[178:181], v186, s[4:5]
	global_load_dwordx4 v[182:185], v186, s[6:7]
	v_mov_b32_e32 v1, 0x30000
	s_waitcnt vmcnt(3)
	v_pk_fma_f32 v[70:71], v[70:71], v[52:53], v[80:81] op_sel_hi:[1,0,0]
	v_pk_fma_f32 v[52:53], v[72:73], v[52:53], v[80:81] op_sel_hi:[1,0,0]
	s_waitcnt vmcnt(2)
	v_pk_mul_f32 v[70:71], v[76:77], v[70:71]
	v_pk_mul_f32 v[52:53], v[78:79], v[52:53]
	v_cvt_pk_bf16_f32 v70, v70, v71
	s_nop 0
	v_cvt_pk_bf16_f32 v71, v52, v53
	global_store_dwordx2 v[60:61], v[70:71], off offset:1024
	s_waitcnt vmcnt(1)
	v_mov_b64_e32 v[70:71], v[178:179]
	v_mov_b64_e32 v[72:73], v[180:181]
	s_nop 0
	v_mov_b64_e32 v[76:77], v[182:183]
	v_mov_b64_e32 v[78:79], v[184:185]
	v_pk_mul_f32 v[52:53], v[18:19], v[54:55] op_sel_hi:[0,1]
	v_pk_fma_f32 v[52:53], v[70:71], v[52:53], v[76:77]
	v_pk_fma_f32 v[54:55], v[72:73], v[58:59], v[78:79]
	global_store_dwordx4 v[84:85], v[52:55], off offset:3072
	global_load_dword v58, v1, s[8:9]
	global_load_dword v76, v67, s[10:11] offset:1536
	global_load_dwordx4 v[70:73], v[90:91], off offset:3072
	v_add_u32_e32 v186, 0x1000, v66
	global_load_dwordx4 v[178:181], v186, s[4:5]
	global_load_dwordx4 v[182:185], v186, s[6:7]
	v_or_b32_e32 v1, 0x1000, v66
	s_waitcnt vmcnt(3)
	v_pk_fma_f32 v[52:53], v[52:53], v[58:59], v[76:77] op_sel_hi:[1,0,0]
	v_pk_fma_f32 v[54:55], v[54:55], v[58:59], v[76:77] op_sel_hi:[1,0,0]
	s_waitcnt vmcnt(2)
	v_pk_mul_f32 v[52:53], v[70:71], v[52:53]
	v_pk_mul_f32 v[54:55], v[72:73], v[54:55]
	v_cvt_pk_bf16_f32 v52, v52, v53
	s_nop 0
	v_cvt_pk_bf16_f32 v53, v54, v55
	global_store_dwordx2 v[60:61], v[52:53], off offset:1536
	s_waitcnt vmcnt(1)
	v_mov_b64_e32 v[52:53], v[178:179]
	v_mov_b64_e32 v[54:55], v[180:181]
	s_nop 0
	v_mov_b64_e32 v[70:71], v[182:183]
	v_mov_b64_e32 v[72:73], v[184:185]
	v_mov_b32_e32 v1, 0x40000
	v_pk_fma_f32 v[52:53], v[52:53], v[56:57], v[70:71]
	v_pk_fma_f32 v[54:55], v[54:55], v[48:49], v[72:73]
	global_store_dwordx4 v[64:65], v[52:55], off
	global_load_dword v48, v1, s[8:9]
	global_load_dword v70, v67, s[10:11] offset:2048
	global_load_dwordx4 v[56:59], v[74:75], off
	v_add_u32_e32 v186, 0x1400, v66
	global_load_dwordx4 v[178:181], v186, s[4:5]
	global_load_dwordx4 v[182:185], v186, s[6:7]
	v_or_b32_e32 v1, 0x1400, v66
	s_waitcnt vmcnt(3)
	v_pk_fma_f32 v[52:53], v[52:53], v[48:49], v[70:71] op_sel_hi:[1,0,0]
	v_pk_fma_f32 v[48:49], v[54:55], v[48:49], v[70:71] op_sel_hi:[1,0,0]
	s_waitcnt vmcnt(2)
	v_pk_mul_f32 v[52:53], v[56:57], v[52:53]
	v_pk_mul_f32 v[48:49], v[58:59], v[48:49]
	v_cvt_pk_bf16_f32 v52, v52, v53
	s_nop 0
	v_cvt_pk_bf16_f32 v53, v48, v49
	global_store_dwordx2 v[60:61], v[52:53], off offset:2048
	s_waitcnt vmcnt(1)
	v_mov_b64_e32 v[52:53], v[178:179]
	v_mov_b64_e32 v[54:55], v[180:181]
	s_nop 0
	v_mov_b64_e32 v[56:57], v[182:183]
	v_mov_b64_e32 v[58:59], v[184:185]
	v_pk_mul_f32 v[48:49], v[18:19], v[50:51] op_sel_hi:[0,1]
	v_mov_b32_e32 v1, 0x50000
	v_pk_fma_f32 v[48:49], v[52:53], v[48:49], v[56:57]
	v_pk_fma_f32 v[50:51], v[54:55], v[44:45], v[58:59]
	global_store_dwordx4 v[64:65], v[48:51], off offset:1024
	global_load_dword v44, v1, s[8:9]
	global_load_dword v56, v67, s[10:11] offset:2560
	global_load_dwordx4 v[52:55], v[74:75], off offset:1024
	v_add_u32_e32 v186, 0x1800, v66
	global_load_dwordx4 v[178:181], v186, s[4:5]
	global_load_dwordx4 v[182:185], v186, s[6:7]
	v_or_b32_e32 v1, 0x1800, v66
	s_waitcnt vmcnt(3)
	v_pk_fma_f32 v[48:49], v[48:49], v[44:45], v[56:57] op_sel_hi:[1,0,0]
	v_pk_fma_f32 v[44:45], v[50:51], v[44:45], v[56:57] op_sel_hi:[1,0,0]
	s_waitcnt vmcnt(2)
	v_pk_mul_f32 v[48:49], v[52:53], v[48:49]
	v_pk_mul_f32 v[44:45], v[54:55], v[44:45]
	v_cvt_pk_bf16_f32 v48, v48, v49
	s_nop 0
	v_cvt_pk_bf16_f32 v49, v44, v45
	global_store_dwordx2 v[60:61], v[48:49], off offset:2560
	s_waitcnt vmcnt(1)
	v_mov_b64_e32 v[48:49], v[178:179]
	v_mov_b64_e32 v[50:51], v[180:181]
	s_nop 0
	v_mov_b64_e32 v[52:53], v[182:183]
	v_mov_b64_e32 v[54:55], v[184:185]
	v_mov_b32_e32 v1, 0x60000
	v_pk_fma_f32 v[44:45], v[48:49], v[38:39], v[52:53]
	v_pk_fma_f32 v[46:47], v[50:51], v[46:47], v[54:55]
	global_store_dwordx4 v[64:65], v[44:47], off offset:2048
	global_load_dword v38, v1, s[8:9]
	global_load_dword v52, v67, s[10:11] offset:3072
	global_load_dwordx4 v[48:51], v[74:75], off offset:2048
	v_add_u32_e32 v186, 0x1c00, v66
	global_load_dwordx4 v[178:181], v186, s[4:5]
	global_load_dwordx4 v[182:185], v186, s[6:7]
	v_or_b32_e32 v1, 0x1c00, v66
	s_waitcnt vmcnt(3)
	v_pk_fma_f32 v[44:45], v[44:45], v[38:39], v[52:53] op_sel_hi:[1,0,0]
	v_pk_fma_f32 v[38:39], v[46:47], v[38:39], v[52:53] op_sel_hi:[1,0,0]
	s_waitcnt vmcnt(2)
	v_pk_mul_f32 v[44:45], v[48:49], v[44:45]
	v_pk_mul_f32 v[38:39], v[50:51], v[38:39]
	v_cvt_pk_bf16_f32 v44, v44, v45
	s_nop 0
	v_cvt_pk_bf16_f32 v45, v38, v39
	global_store_dwordx2 v[60:61], v[44:45], off offset:3072
	s_waitcnt vmcnt(1)
	v_mov_b64_e32 v[44:45], v[178:179]
	v_mov_b64_e32 v[46:47], v[180:181]
	s_nop 0
	v_mov_b64_e32 v[48:49], v[182:183]
	v_mov_b64_e32 v[50:51], v[184:185]
	v_pk_mul_f32 v[38:39], v[18:19], v[36:37] op_sel_hi:[0,1]
	v_pk_mul_f32 v[36:37], v[18:19], v[42:43] op_sel_hi:[0,1]
	v_mov_b32_e32 v1, 0x70000
	v_mov_b32_e32 v19, 0x1000
	v_pk_mul_f32 v[32:33], v[18:19], v[32:33] op_sel_hi:[0,1]
	v_pk_mul_f32 v[34:35], v[18:19], v[34:35] op_sel_hi:[0,1]
	v_pk_mul_f32 v[26:27], v[18:19], v[26:27] op_sel_hi:[0,1]
	v_pk_mul_f32 v[16:17], v[18:19], v[16:17] op_sel_hi:[0,1]
	v_pk_mul_f32 v[14:15], v[18:19], v[14:15] op_sel_hi:[0,1]
	v_pk_mul_f32 v[12:13], v[18:19], v[12:13] op_sel_hi:[0,1]
	v_pk_mul_f32 v[10:11], v[18:19], v[10:11] op_sel_hi:[0,1]
	v_pk_mul_f32 v[8:9], v[18:19], v[8:9] op_sel_hi:[0,1]
	v_pk_mul_f32 v[6:7], v[18:19], v[6:7] op_sel_hi:[0,1]
	v_pk_mul_f32 v[4:5], v[18:19], v[4:5] op_sel_hi:[0,1]
	v_pk_mul_f32 v[2:3], v[18:19], v[2:3] op_sel_hi:[0,1]
	v_pk_fma_f32 v[36:37], v[44:45], v[36:37], v[48:49]
	v_pk_fma_f32 v[38:39], v[46:47], v[38:39], v[50:51]
	global_store_dwordx4 v[64:65], v[36:39], off offset:3072
	global_load_dword v46, v1, s[8:9]
	global_load_dword v48, v67, s[10:11] offset:3584
	global_load_dwordx4 v[42:45], v[74:75], off offset:3072
	v_add_u32_e32 v186, 0x2000, v66
	global_load_dwordx4 v[178:181], v186, s[4:5]
	global_load_dwordx4 v[182:185], v186, s[6:7]
	v_or_b32_e32 v1, 0x2000, v66
	s_waitcnt vmcnt(3)
	v_pk_fma_f32 v[36:37], v[36:37], v[46:47], v[48:49] op_sel_hi:[1,0,0]
	v_pk_fma_f32 v[38:39], v[38:39], v[46:47], v[48:49] op_sel_hi:[1,0,0]
	s_waitcnt vmcnt(2)
	v_pk_mul_f32 v[36:37], v[42:43], v[36:37]
	v_pk_mul_f32 v[38:39], v[44:45], v[38:39]
	v_cvt_pk_bf16_f32 v36, v36, v37
	s_nop 0
	v_cvt_pk_bf16_f32 v37, v38, v39
	global_store_dwordx2 v[60:61], v[36:37], off offset:3584
	s_waitcnt vmcnt(1)
	v_mov_b64_e32 v[42:43], v[178:179]
	v_mov_b64_e32 v[44:45], v[180:181]
	v_mov_b64_e32 v[46:47], v[182:183]
	v_mov_b64_e32 v[48:49], v[184:185]
	v_add_co_u32_e32 v36, vcc, s0, v62
	v_pk_mul_f32 v[38:39], v[18:19], v[40:41] op_sel_hi:[0,1]
	s_nop 0
	v_addc_co_u32_e32 v37, vcc, 0, v63, vcc
	v_mov_b32_e32 v1, 0x80000
	s_mov_b32 s0, 0x8882000
	v_pk_fma_f32 v[38:39], v[42:43], v[38:39], v[46:47]
	v_pk_fma_f32 v[40:41], v[44:45], v[32:33], v[48:49]
	global_store_dwordx4 v[36:37], v[38:41], off offset:-4096
	v_add_co_u32_e32 v32, vcc, s1, v68
	global_load_dword v46, v1, s[8:9]
	global_load_dword v48, v19, s[10:11]
	v_addc_co_u32_e32 v33, vcc, 0, v69, vcc
	global_load_dwordx4 v[42:45], v[32:33], off offset:-4096
	v_add_u32_e32 v186, 0x2400, v66
	global_load_dwordx4 v[178:181], v186, s[4:5]
	global_load_dwordx4 v[182:185], v186, s[6:7]
	v_or_b32_e32 v1, 0x2400, v66
	s_mov_b32 s1, 0x69982000
	s_waitcnt vmcnt(3)
	v_pk_fma_f32 v[38:39], v[38:39], v[46:47], v[48:49] op_sel_hi:[1,0,0]
	v_pk_fma_f32 v[40:41], v[40:41], v[46:47], v[48:49] op_sel_hi:[1,0,0]
	v_add_co_u32_e32 v46, vcc, s0, v62
	s_waitcnt vmcnt(2)
	v_pk_mul_f32 v[38:39], v[42:43], v[38:39]
	v_pk_mul_f32 v[40:41], v[44:45], v[40:41]
	v_cvt_pk_bf16_f32 v38, v38, v39
	v_addc_co_u32_e32 v47, vcc, 0, v63, vcc
	v_cvt_pk_bf16_f32 v39, v40, v41
	global_store_dwordx2 v[28:29], v[38:39], off
	s_waitcnt vmcnt(1)
	v_mov_b64_e32 v[38:39], v[178:179]
	v_mov_b64_e32 v[40:41], v[180:181]
	s_nop 0
	v_mov_b64_e32 v[42:43], v[182:183]
	v_mov_b64_e32 v[44:45], v[184:185]
	v_mov_b32_e32 v1, 0x90000
	v_add_co_u32_e32 v48, vcc, s1, v68
	v_pk_fma_f32 v[38:39], v[38:39], v[26:27], v[42:43]
	v_pk_fma_f32 v[40:41], v[40:41], v[34:35], v[44:45]
	global_store_dwordx4 v[46:47], v[38:41], off offset:1024
	global_load_dword v26, v1, s[8:9]
	global_load_dword v34, v19, s[10:11] offset:512
	v_addc_co_u32_e32 v49, vcc, 0, v69, vcc
	global_load_dwordx4 v[42:45], v[48:49], off offset:1024
	v_add_u32_e32 v186, 0x2800, v66
	global_load_dwordx4 v[178:181], v186, s[4:5]
	global_load_dwordx4 v[182:185], v186, s[6:7]
	v_or_b32_e32 v1, 0x2800, v66
	s_waitcnt vmcnt(3)
	v_pk_fma_f32 v[38:39], v[38:39], v[26:27], v[34:35] op_sel_hi:[1,0,0]
	v_pk_fma_f32 v[26:27], v[40:41], v[26:27], v[34:35] op_sel_hi:[1,0,0]
	s_waitcnt vmcnt(2)
	v_pk_mul_f32 v[34:35], v[42:43], v[38:39]
	v_pk_mul_f32 v[26:27], v[44:45], v[26:27]
	v_cvt_pk_bf16_f32 v34, v34, v35
	s_nop 0
	v_cvt_pk_bf16_f32 v35, v26, v27
	global_store_dwordx2 v[28:29], v[34:35], off offset:512
	s_waitcnt vmcnt(1)
	v_mov_b64_e32 v[38:39], v[178:179]
	v_mov_b64_e32 v[40:41], v[180:181]
	v_mov_b64_e32 v[42:43], v[182:183]
	v_mov_b64_e32 v[44:45], v[184:185]
	v_pk_mul_f32 v[26:27], v[18:19], v[24:25] op_sel_hi:[0,1]
	v_pk_mul_f32 v[24:25], v[18:19], v[30:31] op_sel_hi:[0,1]
	v_mov_b32_e32 v1, 0xa0000
	v_pk_fma_f32 v[24:25], v[38:39], v[24:25], v[42:43]
	v_pk_fma_f32 v[26:27], v[40:41], v[26:27], v[44:45]
	global_store_dwordx4 v[46:47], v[24:27], off offset:2048
	global_load_dword v30, v1, s[8:9]
	global_load_dword v34, v19, s[10:11] offset:1024
	global_load_dwordx4 v[38:41], v[48:49], off offset:2048
	v_add_u32_e32 v186, 0x2c00, v66
	global_load_dwordx4 v[178:181], v186, s[4:5]
	global_load_dwordx4 v[182:185], v186, s[6:7]
	v_or_b32_e32 v1, 0x2c00, v66
	s_waitcnt vmcnt(3)
	v_pk_fma_f32 v[24:25], v[24:25], v[30:31], v[34:35] op_sel_hi:[1,0,0]
	v_pk_fma_f32 v[26:27], v[26:27], v[30:31], v[34:35] op_sel_hi:[1,0,0]
	s_waitcnt vmcnt(2)
	v_pk_mul_f32 v[24:25], v[38:39], v[24:25]
	v_pk_mul_f32 v[26:27], v[40:41], v[26:27]
	v_cvt_pk_bf16_f32 v24, v24, v25
	v_pk_mul_f32 v[30:31], v[18:19], v[20:21] op_sel_hi:[0,1]
	v_cvt_pk_bf16_f32 v25, v26, v27
	global_store_dwordx2 v[28:29], v[24:25], off offset:1024
	s_waitcnt vmcnt(1)
	v_mov_b64_e32 v[24:25], v[178:179]
	v_mov_b64_e32 v[26:27], v[180:181]
	s_nop 0
	v_mov_b64_e32 v[38:39], v[182:183]
	v_mov_b64_e32 v[40:41], v[184:185]
	v_pk_mul_f32 v[20:21], v[18:19], v[22:23] op_sel_hi:[0,1]
	v_mov_b32_e32 v1, 0xb0000
	v_pk_fma_f32 v[20:21], v[24:25], v[20:21], v[38:39]
	v_pk_fma_f32 v[22:23], v[26:27], v[30:31], v[40:41]
	global_store_dwordx4 v[46:47], v[20:23], off offset:3072
	global_load_dword v30, v1, s[8:9]
	global_load_dword v34, v19, s[10:11] offset:1536
	global_load_dwordx4 v[24:27], v[48:49], off offset:3072
	v_add_u32_e32 v186, 0x3000, v66
	global_load_dwordx4 v[178:181], v186, s[4:5]
	global_load_dwordx4 v[182:185], v186, s[6:7]
	v_or_b32_e32 v1, 0x3000, v66
	s_waitcnt vmcnt(3)
	v_pk_fma_f32 v[20:21], v[20:21], v[30:31], v[34:35] op_sel_hi:[1,0,0]
	v_pk_fma_f32 v[22:23], v[22:23], v[30:31], v[34:35] op_sel_hi:[1,0,0]
	s_waitcnt vmcnt(2)
	v_pk_mul_f32 v[20:21], v[24:25], v[20:21]
	v_pk_mul_f32 v[22:23], v[26:27], v[22:23]
	v_cvt_pk_bf16_f32 v20, v20, v21
	s_nop 0
	v_cvt_pk_bf16_f32 v21, v22, v23
	global_store_dwordx2 v[28:29], v[20:21], off offset:1536
	s_waitcnt vmcnt(1)
	v_mov_b64_e32 v[20:21], v[178:179]
	v_mov_b64_e32 v[22:23], v[180:181]
	s_nop 0
	v_mov_b64_e32 v[24:25], v[182:183]
	v_mov_b64_e32 v[26:27], v[184:185]
	v_mov_b32_e32 v1, 0xc0000
	v_pk_fma_f32 v[14:15], v[20:21], v[14:15], v[24:25]
	v_pk_fma_f32 v[16:17], v[22:23], v[16:17], v[26:27]
	global_store_dwordx4 v[36:37], v[14:17], off
	global_load_dword v24, v1, s[8:9]
	global_load_dword v26, v19, s[10:11] offset:2048
	global_load_dwordx4 v[20:23], v[32:33], off
	v_add_u32_e32 v186, 0x3400, v66
	global_load_dwordx4 v[178:181], v186, s[4:5]
	global_load_dwordx4 v[182:185], v186, s[6:7]
	v_or_b32_e32 v1, 0x3400, v66
	s_waitcnt vmcnt(3)
	v_pk_fma_f32 v[14:15], v[14:15], v[24:25], v[26:27] op_sel_hi:[1,0,0]
	v_pk_fma_f32 v[16:17], v[16:17], v[24:25], v[26:27] op_sel_hi:[1,0,0]
	s_waitcnt vmcnt(2)
	v_pk_mul_f32 v[14:15], v[20:21], v[14:15]
	v_pk_mul_f32 v[16:17], v[22:23], v[16:17]
	v_cvt_pk_bf16_f32 v14, v14, v15
	s_nop 0
	v_cvt_pk_bf16_f32 v15, v16, v17
	global_store_dwordx2 v[28:29], v[14:15], off offset:2048
	s_waitcnt vmcnt(1)
	v_mov_b64_e32 v[14:15], v[178:179]
	v_mov_b64_e32 v[16:17], v[180:181]
	s_nop 0
	v_mov_b64_e32 v[20:21], v[182:183]
	v_mov_b64_e32 v[22:23], v[184:185]
	v_mov_b32_e32 v1, 0xd0000
	v_pk_fma_f32 v[10:11], v[14:15], v[10:11], v[20:21]
	v_pk_fma_f32 v[12:13], v[16:17], v[12:13], v[22:23]
	global_store_dwordx4 v[36:37], v[10:13], off offset:1024
	global_load_dword v20, v1, s[8:9]
	global_load_dword v22, v19, s[10:11] offset:2560
	global_load_dwordx4 v[14:17], v[32:33], off offset:1024
	v_add_u32_e32 v186, 0x3800, v66
	global_load_dwordx4 v[178:181], v186, s[4:5]
	global_load_dwordx4 v[182:185], v186, s[6:7]
	v_or_b32_e32 v1, 0x3800, v66
	s_waitcnt vmcnt(3)
	v_pk_fma_f32 v[10:11], v[10:11], v[20:21], v[22:23] op_sel_hi:[1,0,0]
	v_pk_fma_f32 v[12:13], v[12:13], v[20:21], v[22:23] op_sel_hi:[1,0,0]
	s_waitcnt vmcnt(2)
	v_pk_mul_f32 v[10:11], v[14:15], v[10:11]
	v_pk_mul_f32 v[12:13], v[16:17], v[12:13]
	v_cvt_pk_bf16_f32 v10, v10, v11
	s_nop 0
	v_cvt_pk_bf16_f32 v11, v12, v13
	global_store_dwordx2 v[28:29], v[10:11], off offset:2560
	s_waitcnt vmcnt(1)
	v_mov_b64_e32 v[10:11], v[178:179]
	v_mov_b64_e32 v[12:13], v[180:181]
	s_nop 0
	v_mov_b64_e32 v[14:15], v[182:183]
	v_mov_b64_e32 v[16:17], v[184:185]
	v_mov_b32_e32 v1, 0xe0000
	v_pk_fma_f32 v[6:7], v[10:11], v[6:7], v[14:15]
	v_pk_fma_f32 v[8:9], v[12:13], v[8:9], v[16:17]
	global_store_dwordx4 v[36:37], v[6:9], off offset:2048
	global_load_dword v14, v1, s[8:9]
	global_load_dword v16, v19, s[10:11] offset:3072
	global_load_dwordx4 v[10:13], v[32:33], off offset:2048
	v_add_u32_e32 v186, 0x3c00, v66
	global_load_dwordx4 v[178:181], v186, s[4:5]
	global_load_dwordx4 v[182:185], v186, s[6:7]
	v_or_b32_e32 v1, 0x3c00, v66
	s_waitcnt vmcnt(3)
	v_pk_fma_f32 v[6:7], v[6:7], v[14:15], v[16:17] op_sel_hi:[1,0,0]
	v_pk_fma_f32 v[8:9], v[8:9], v[14:15], v[16:17] op_sel_hi:[1,0,0]
	s_waitcnt vmcnt(2)
	v_pk_mul_f32 v[6:7], v[10:11], v[6:7]
	v_pk_mul_f32 v[8:9], v[12:13], v[8:9]
	v_cvt_pk_bf16_f32 v6, v6, v7
	s_nop 0
	v_cvt_pk_bf16_f32 v7, v8, v9
	global_store_dwordx2 v[28:29], v[6:7], off offset:3072
	s_waitcnt vmcnt(1)
	v_mov_b64_e32 v[6:7], v[178:179]
	v_mov_b64_e32 v[8:9], v[180:181]
	s_nop 0
	v_mov_b64_e32 v[10:11], v[182:183]
	v_mov_b64_e32 v[12:13], v[184:185]
	v_mov_b32_e32 v1, 0xf0000
	v_pk_fma_f32 v[2:3], v[6:7], v[2:3], v[10:11]
	v_pk_fma_f32 v[4:5], v[8:9], v[4:5], v[12:13]
	global_store_dwordx4 v[36:37], v[2:5], off offset:3072
	global_load_dword v10, v1, s[8:9]
	global_load_dword v12, v19, s[10:11] offset:3584
	global_load_dwordx4 v[6:9], v[32:33], off offset:3072
	s_waitcnt vmcnt(1)
	v_pk_fma_f32 v[2:3], v[2:3], v[10:11], v[12:13] op_sel_hi:[1,0,0]
	v_pk_fma_f32 v[4:5], v[4:5], v[10:11], v[12:13] op_sel_hi:[1,0,0]
	s_waitcnt vmcnt(0)
	v_pk_mul_f32 v[2:3], v[6:7], v[2:3]
	v_pk_mul_f32 v[4:5], v[8:9], v[4:5]
	v_cvt_pk_bf16_f32 v2, v2, v3
	s_nop 0
	v_cvt_pk_bf16_f32 v3, v4, v5
	global_store_dwordx2 v[28:29], v[2:3], off offset:3584
